# v116 + P6 residual epilogue: the four x loads of each 16-row block issued together (second group into free registers), counted waits
# speedup vs baseline: 1.0017x; 1.0017x over previous
.LBB0_1022:
	v_mov_b32_e32 v142, v146
	v_mov_b32_e32 v143, v1
	v_mov_b32_e32 v153, v147
	v_mov_b32_e32 v144, v165
	s_lshl_b32 s1, s24, 8
	s_add_i32 s1, s1, s39
	v_add_u32_e32 v144, s1, v142
	s_lshl_b32 s0, s0, 8
	s_or_b32 s0, s0, s40
	v_ashrrev_i32_e32 v145, 31, v144
	v_lshl_add_u32 v142, v153, 3, s0
	v_lshlrev_b64 v[154:155], 13, v[144:145]
	v_lshl_add_u64 v[154:155], s[60:61], 0, v[154:155]
	v_ashrrev_i32_e32 v143, 31, v142
	v_lshl_add_u64 v[162:163], v[142:143], 2, v[154:155]
	global_load_dwordx4 v[154:157], v[162:163], off
	global_load_dwordx4 v[158:161], v[162:163], off offset:16
	global_load_dwordx4 v[170:173], v[162:163], off offset:512
	global_load_dwordx4 v[174:177], v[162:163], off offset:528
	v_lshlrev_b64 v[166:167], 12, v[144:145]
	v_lshl_add_u64 v[166:167], s[62:63], 0, v[166:167]
	v_lshl_add_u64 v[166:167], v[142:143], 1, v[166:167]
	v_cmp_eq_u32_e32 vcc, 0, v153
	s_waitcnt vmcnt(2)
	v_pk_add_f32 v[128:129], v[128:129], v[156:157]
	v_pk_add_f32 v[168:169], v[126:127], v[154:155]
	v_pk_add_f32 v[160:161], v[124:125], v[160:161]
	v_pk_add_f32 v[158:159], v[122:123], v[158:159]
	v_cvt_pk_bf16_f32 v122, v168, v169
	v_cvt_pk_bf16_f32 v123, v128, v129
	v_mul_f32_e32 v153, v169, v169
	v_cvt_pk_bf16_f32 v124, v158, v159
	v_cvt_pk_bf16_f32 v125, v160, v161
	global_store_dwordx4 v[166:167], v[122:125], off
	s_nop 0
	s_nop 0
	s_nop 0
	v_mul_f32_e32 v129, v129, v129
	v_mul_f32_e32 v159, v159, v159
	v_fmac_f32_e32 v153, v168, v168
	v_fmac_f32_e32 v129, v128, v128
	v_mul_f32_e32 v161, v161, v161
	v_fmac_f32_e32 v159, v158, v158
	v_add_f32_e32 v128, v153, v129
	v_fmac_f32_e32 v161, v160, v160
	v_add_f32_e32 v128, v128, v159
	v_add_f32_e32 v153, v161, v128
	v_and_b32_e32 v123, 64, v152
	v_xor_b32_e32 v122, 16, v152
	v_add_u32_e32 v123, 64, v123
	v_cmp_lt_i32_e64 s[0:1], v122, v123
	v_xor_b32_e32 v162, 32, v152
	s_waitcnt vmcnt(2)
	v_pk_add_f32 v[120:121], v[120:121], v[172:173]
	v_pk_add_f32 v[118:119], v[118:119], v[170:171]
	s_waitcnt vmcnt(1)
	v_pk_add_f32 v[128:129], v[116:117], v[176:177]
	v_pk_add_f32 v[114:115], v[114:115], v[174:175]
	v_mul_f32_e32 v116, v119, v119
	v_mul_f32_e32 v117, v121, v121
	v_mul_f32_e32 v124, v115, v115
	v_fmac_f32_e32 v116, v118, v118
	v_fmac_f32_e32 v117, v120, v120
	v_mul_f32_e32 v125, v129, v129
	v_fmac_f32_e32 v124, v114, v114
	v_add_f32_e32 v116, v116, v117
	v_fmac_f32_e32 v125, v128, v128
	v_add_f32_e32 v116, v116, v124
	v_cndmask_b32_e64 v122, v152, v122, s[0:1]
	v_add_f32_e32 v116, v125, v116
	v_lshlrev_b32_e32 v122, 2, v122
	v_add_f32_e32 v116, v153, v116
	ds_bpermute_b32 v117, v122, v116
	v_cmp_lt_i32_e64 s[0:1], v162, v123
	v_cvt_pk_bf16_f32 v124, v118, v119
	v_cvt_pk_bf16_f32 v125, v120, v121
	v_cvt_pk_bf16_f32 v126, v114, v115
	s_waitcnt lgkmcnt(0)
	v_add_f32_e32 v117, v116, v117
	v_lshl_add_u64 v[114:115], v[144:145], 2, s[84:85]
	v_cndmask_b32_e64 v123, v152, v162, s[0:1]
	v_lshlrev_b32_e32 v116, 2, v123
	ds_bpermute_b32 v118, v116, v117
	v_cvt_pk_bf16_f32 v127, v128, v129
	global_store_dwordx4 v[166:167], v[124:127], off offset:256
	s_and_saveexec_b64 s[0:1], vcc
	s_cbranch_execz .LBB0_1024
	s_waitcnt lgkmcnt(0)
	v_add_f32_e32 v117, v117, v118
	global_atomic_add_f32 v[114:115], v117, off
.LBB0_1024:
	s_or_b64 exec, exec, s[0:1]
	v_add_u32_e32 v128, 16, v144
	v_ashrrev_i32_e32 v129, 31, v128
	s_waitcnt lgkmcnt(0)
	v_lshlrev_b64 v[118:119], 13, v[128:129]
	v_lshl_add_u64 v[118:119], s[60:61], 0, v[118:119]
	v_lshl_add_u64 v[154:155], v[142:143], 2, v[118:119]
	global_load_dwordx4 v[118:121], v[154:155], off
	global_load_dwordx4 v[124:127], v[154:155], off offset:16
	global_load_dwordx4 v[170:173], v[154:155], off offset:512
	global_load_dwordx4 v[174:177], v[154:155], off offset:528
	v_lshlrev_b64 v[128:129], 12, v[128:129]
	v_lshl_add_u64 v[128:129], s[62:63], 0, v[128:129]
	v_lshl_add_u64 v[128:129], v[142:143], 1, v[128:129]
	s_waitcnt vmcnt(3)
	v_pk_add_f32 v[120:121], v[112:113], v[120:121]
	v_pk_add_f32 v[118:119], v[110:111], v[118:119]
	s_waitcnt vmcnt(2)
	v_pk_add_f32 v[126:127], v[108:109], v[126:127]
	v_pk_add_f32 v[124:125], v[106:107], v[124:125]
	v_cvt_pk_bf16_f32 v106, v118, v119
	v_cvt_pk_bf16_f32 v107, v120, v121
	v_mul_f32_e32 v117, v119, v119
	v_cvt_pk_bf16_f32 v108, v124, v125
	v_cvt_pk_bf16_f32 v109, v126, v127
	global_store_dwordx4 v[128:129], v[106:109], off
	s_nop 0
	s_nop 0
	s_nop 0
	v_mul_f32_e32 v119, v121, v121
	v_mul_f32_e32 v121, v125, v125
	v_fmac_f32_e32 v117, v118, v118
	v_fmac_f32_e32 v119, v120, v120
	v_mul_f32_e32 v123, v127, v127
	v_fmac_f32_e32 v121, v124, v124
	v_add_f32_e32 v117, v117, v119
	v_fmac_f32_e32 v123, v126, v126
	v_add_f32_e32 v117, v117, v121
	v_add_f32_e32 v117, v123, v117
	s_waitcnt vmcnt(2)
	v_pk_add_f32 v[104:105], v[104:105], v[172:173]
	v_pk_add_f32 v[102:103], v[102:103], v[170:171]
	s_waitcnt vmcnt(1)
	v_pk_add_f32 v[108:109], v[98:99], v[174:175]
	v_mul_f32_e32 v98, v103, v103
	v_mul_f32_e32 v99, v105, v105
	v_pk_add_f32 v[106:107], v[100:101], v[176:177]
	v_mul_f32_e32 v100, v109, v109
	v_fmac_f32_e32 v98, v102, v102
	v_fmac_f32_e32 v99, v104, v104
	v_mul_f32_e32 v101, v107, v107
	v_fmac_f32_e32 v100, v108, v108
	v_add_f32_e32 v98, v98, v99
	v_add_f32_e32 v98, v98, v100
	v_fmac_f32_e32 v101, v106, v106
	v_add_f32_e32 v98, v101, v98
	v_add_f32_e32 v98, v117, v98
	ds_bpermute_b32 v99, v122, v98
	v_cvt_pk_bf16_f32 v100, v102, v103
	v_cvt_pk_bf16_f32 v101, v104, v105
	v_cvt_pk_bf16_f32 v102, v108, v109
	v_cvt_pk_bf16_f32 v103, v106, v107
	s_waitcnt lgkmcnt(0)
	v_add_f32_e32 v98, v98, v99
	ds_bpermute_b32 v99, v116, v98
	global_store_dwordx4 v[128:129], v[100:103], off offset:256
	s_and_saveexec_b64 s[0:1], vcc
	s_cbranch_execz .LBB0_1026
	s_waitcnt lgkmcnt(0)
	v_add_f32_e32 v98, v98, v99
	global_atomic_add_f32 v[114:115], v98, off offset:64
.LBB0_1026:
	s_or_b64 exec, exec, s[0:1]
	v_add_u32_e32 v106, 32, v144
	v_ashrrev_i32_e32 v107, 31, v106
	s_waitcnt lgkmcnt(0)
	v_lshlrev_b64 v[98:99], 13, v[106:107]
	v_lshl_add_u64 v[98:99], s[60:61], 0, v[98:99]
	v_lshl_add_u64 v[108:109], v[142:143], 2, v[98:99]
	global_load_dwordx4 v[98:101], v[108:109], off
	global_load_dwordx4 v[102:105], v[108:109], off offset:16
	global_load_dwordx4 v[170:173], v[108:109], off offset:512
	global_load_dwordx4 v[174:177], v[108:109], off offset:528
	v_lshlrev_b64 v[106:107], 12, v[106:107]
	v_lshl_add_u64 v[106:107], s[62:63], 0, v[106:107]
	v_lshl_add_u64 v[106:107], v[142:143], 1, v[106:107]
	s_waitcnt vmcnt(3)
	v_pk_add_f32 v[100:101], v[96:97], v[100:101]
	v_pk_add_f32 v[98:99], v[94:95], v[98:99]
	s_waitcnt vmcnt(2)
	v_pk_add_f32 v[104:105], v[92:93], v[104:105]
	v_pk_add_f32 v[102:103], v[90:91], v[102:103]
	v_cvt_pk_bf16_f32 v90, v98, v99
	v_cvt_pk_bf16_f32 v91, v100, v101
	v_mul_f32_e32 v99, v99, v99
	v_cvt_pk_bf16_f32 v92, v102, v103
	v_cvt_pk_bf16_f32 v93, v104, v105
	global_store_dwordx4 v[106:107], v[90:93], off
	s_nop 0
	s_nop 0
	s_nop 0
	v_mul_f32_e32 v101, v101, v101
	v_mul_f32_e32 v103, v103, v103
	v_fmac_f32_e32 v99, v98, v98
	v_fmac_f32_e32 v101, v100, v100
	v_mul_f32_e32 v105, v105, v105
	v_fmac_f32_e32 v103, v102, v102
	v_add_f32_e32 v98, v99, v101
	v_fmac_f32_e32 v105, v104, v104
	v_add_f32_e32 v98, v98, v103
	v_add_f32_e32 v98, v105, v98
	s_waitcnt vmcnt(2)
	v_pk_add_f32 v[88:89], v[88:89], v[172:173]
	v_pk_add_f32 v[86:87], v[86:87], v[170:171]
	s_waitcnt vmcnt(1)
	v_pk_add_f32 v[92:93], v[82:83], v[174:175]
	v_mul_f32_e32 v82, v87, v87
	v_mul_f32_e32 v83, v89, v89
	v_pk_add_f32 v[90:91], v[84:85], v[176:177]
	v_mul_f32_e32 v84, v93, v93
	v_fmac_f32_e32 v82, v86, v86
	v_fmac_f32_e32 v83, v88, v88
	v_mul_f32_e32 v85, v91, v91
	v_fmac_f32_e32 v84, v92, v92
	v_add_f32_e32 v82, v82, v83
	v_add_f32_e32 v82, v82, v84
	v_fmac_f32_e32 v85, v90, v90
	v_add_f32_e32 v82, v85, v82
	v_add_f32_e32 v82, v98, v82
	ds_bpermute_b32 v83, v122, v82
	v_cvt_pk_bf16_f32 v84, v86, v87
	v_cvt_pk_bf16_f32 v85, v88, v89
	v_cvt_pk_bf16_f32 v86, v92, v93
	v_cvt_pk_bf16_f32 v87, v90, v91
	s_waitcnt lgkmcnt(0)
	v_add_f32_e32 v82, v82, v83
	ds_bpermute_b32 v83, v116, v82
	global_store_dwordx4 v[106:107], v[84:87], off offset:256
	s_and_saveexec_b64 s[0:1], vcc
	s_cbranch_execz .LBB0_1028
	s_waitcnt lgkmcnt(0)
	v_add_f32_e32 v82, v82, v83
	global_atomic_add_f32 v[114:115], v82, off offset:128
.LBB0_1028:
	s_or_b64 exec, exec, s[0:1]
	v_add_u32_e32 v90, 48, v144
	v_ashrrev_i32_e32 v91, 31, v90
	s_waitcnt lgkmcnt(0)
	v_lshlrev_b64 v[82:83], 13, v[90:91]
	v_lshl_add_u64 v[82:83], s[60:61], 0, v[82:83]
	v_lshl_add_u64 v[92:93], v[142:143], 2, v[82:83]
	global_load_dwordx4 v[82:85], v[92:93], off
	global_load_dwordx4 v[86:89], v[92:93], off offset:16
	global_load_dwordx4 v[170:173], v[92:93], off offset:512
	global_load_dwordx4 v[174:177], v[92:93], off offset:528
	v_lshlrev_b64 v[90:91], 12, v[90:91]
	v_lshl_add_u64 v[90:91], s[62:63], 0, v[90:91]
	v_lshl_add_u64 v[90:91], v[142:143], 1, v[90:91]
	s_waitcnt vmcnt(3)
	v_pk_add_f32 v[84:85], v[80:81], v[84:85]
	v_pk_add_f32 v[82:83], v[78:79], v[82:83]
	s_waitcnt vmcnt(2)
	v_pk_add_f32 v[88:89], v[76:77], v[88:89]
	v_pk_add_f32 v[86:87], v[74:75], v[86:87]
	v_cvt_pk_bf16_f32 v74, v82, v83
	v_cvt_pk_bf16_f32 v75, v84, v85
	v_mul_f32_e32 v83, v83, v83
	v_cvt_pk_bf16_f32 v76, v86, v87
	v_cvt_pk_bf16_f32 v77, v88, v89
	global_store_dwordx4 v[90:91], v[74:77], off
	s_nop 0
	s_nop 0
	s_nop 0
	v_mul_f32_e32 v85, v85, v85
	v_mul_f32_e32 v87, v87, v87
	v_fmac_f32_e32 v83, v82, v82
	v_fmac_f32_e32 v85, v84, v84
	v_mul_f32_e32 v89, v89, v89
	v_fmac_f32_e32 v87, v86, v86
	v_add_f32_e32 v82, v83, v85
	v_fmac_f32_e32 v89, v88, v88
	v_add_f32_e32 v82, v82, v87
	v_add_f32_e32 v82, v89, v82
	s_waitcnt vmcnt(2)
	v_pk_add_f32 v[72:73], v[72:73], v[172:173]
	v_pk_add_f32 v[70:71], v[70:71], v[170:171]
	s_waitcnt vmcnt(1)
	v_pk_add_f32 v[76:77], v[66:67], v[174:175]
	v_mul_f32_e32 v66, v71, v71
	v_mul_f32_e32 v67, v73, v73
	v_pk_add_f32 v[74:75], v[68:69], v[176:177]
	v_mul_f32_e32 v68, v77, v77
	v_fmac_f32_e32 v66, v70, v70
	v_fmac_f32_e32 v67, v72, v72
	v_mul_f32_e32 v69, v75, v75
	v_fmac_f32_e32 v68, v76, v76
	v_add_f32_e32 v66, v66, v67
	v_add_f32_e32 v66, v66, v68
	v_fmac_f32_e32 v69, v74, v74
	v_add_f32_e32 v66, v69, v66
	v_add_f32_e32 v66, v82, v66
	ds_bpermute_b32 v67, v122, v66
	v_cvt_pk_bf16_f32 v68, v70, v71
	v_cvt_pk_bf16_f32 v69, v72, v73
	v_cvt_pk_bf16_f32 v70, v76, v77
	v_cvt_pk_bf16_f32 v71, v74, v75
	s_waitcnt lgkmcnt(0)
	v_add_f32_e32 v66, v66, v67
	ds_bpermute_b32 v67, v116, v66
	global_store_dwordx4 v[90:91], v[68:71], off offset:256
	s_and_saveexec_b64 s[0:1], vcc
	s_cbranch_execz .LBB0_1030
	s_waitcnt lgkmcnt(0)
	v_add_f32_e32 v66, v66, v67
	global_atomic_add_f32 v[114:115], v66, off offset:192
.LBB0_1030:
	s_or_b64 exec, exec, s[0:1]
	v_add_u32_e32 v74, 0x80, v144
	v_ashrrev_i32_e32 v75, 31, v74
	s_waitcnt lgkmcnt(0)
	v_lshlrev_b64 v[66:67], 13, v[74:75]
	v_lshl_add_u64 v[66:67], s[60:61], 0, v[66:67]
	v_lshl_add_u64 v[76:77], v[142:143], 2, v[66:67]
	global_load_dwordx4 v[66:69], v[76:77], off
	global_load_dwordx4 v[70:73], v[76:77], off offset:16
	global_load_dwordx4 v[170:173], v[76:77], off offset:512
	global_load_dwordx4 v[174:177], v[76:77], off offset:528
	v_lshlrev_b64 v[74:75], 12, v[74:75]
	v_lshl_add_u64 v[74:75], s[62:63], 0, v[74:75]
	v_lshl_add_u64 v[74:75], v[142:143], 1, v[74:75]
	s_waitcnt vmcnt(3)
	v_pk_add_f32 v[68:69], v[64:65], v[68:69]
	v_pk_add_f32 v[66:67], v[62:63], v[66:67]
	s_waitcnt vmcnt(2)
	v_pk_add_f32 v[72:73], v[60:61], v[72:73]
	v_pk_add_f32 v[70:71], v[58:59], v[70:71]
	v_cvt_pk_bf16_f32 v58, v66, v67
	v_cvt_pk_bf16_f32 v59, v68, v69
	v_mul_f32_e32 v67, v67, v67
	v_cvt_pk_bf16_f32 v60, v70, v71
	v_cvt_pk_bf16_f32 v61, v72, v73
	global_store_dwordx4 v[74:75], v[58:61], off
	s_nop 0
	s_nop 0
	s_nop 0
	v_mul_f32_e32 v69, v69, v69
	v_mul_f32_e32 v71, v71, v71
	v_fmac_f32_e32 v67, v66, v66
	v_fmac_f32_e32 v69, v68, v68
	v_mul_f32_e32 v73, v73, v73
	v_fmac_f32_e32 v71, v70, v70
	v_add_f32_e32 v66, v67, v69
	v_fmac_f32_e32 v73, v72, v72
	v_add_f32_e32 v66, v66, v71
	v_add_f32_e32 v66, v73, v66
	s_waitcnt vmcnt(2)
	v_pk_add_f32 v[56:57], v[56:57], v[172:173]
	v_pk_add_f32 v[54:55], v[54:55], v[170:171]
	s_waitcnt vmcnt(1)
	v_pk_add_f32 v[60:61], v[50:51], v[174:175]
	v_mul_f32_e32 v50, v55, v55
	v_mul_f32_e32 v51, v57, v57
	v_pk_add_f32 v[58:59], v[52:53], v[176:177]
	v_mul_f32_e32 v52, v61, v61
	v_fmac_f32_e32 v50, v54, v54
	v_fmac_f32_e32 v51, v56, v56
	v_mul_f32_e32 v53, v59, v59
	v_fmac_f32_e32 v52, v60, v60
	v_add_f32_e32 v50, v50, v51
	v_add_f32_e32 v50, v50, v52
	v_fmac_f32_e32 v53, v58, v58
	v_add_f32_e32 v50, v53, v50
	v_add_f32_e32 v50, v66, v50
	ds_bpermute_b32 v51, v122, v50
	v_cvt_pk_bf16_f32 v52, v54, v55
	v_cvt_pk_bf16_f32 v53, v56, v57
	v_cvt_pk_bf16_f32 v54, v60, v61
	v_cvt_pk_bf16_f32 v55, v58, v59
	s_waitcnt lgkmcnt(0)
	v_add_f32_e32 v50, v50, v51
	ds_bpermute_b32 v51, v116, v50
	global_store_dwordx4 v[74:75], v[52:55], off offset:256
	s_and_saveexec_b64 s[0:1], vcc
	s_cbranch_execz .LBB0_1032
	s_waitcnt lgkmcnt(0)
	v_add_f32_e32 v50, v50, v51
	global_atomic_add_f32 v[114:115], v50, off offset:512
.LBB0_1032:
	s_or_b64 exec, exec, s[0:1]
	v_add_u32_e32 v58, 0x90, v144
	v_ashrrev_i32_e32 v59, 31, v58
	s_waitcnt lgkmcnt(0)
	v_lshlrev_b64 v[50:51], 13, v[58:59]
	v_lshl_add_u64 v[50:51], s[60:61], 0, v[50:51]
	v_lshl_add_u64 v[60:61], v[142:143], 2, v[50:51]
	global_load_dwordx4 v[50:53], v[60:61], off
	global_load_dwordx4 v[54:57], v[60:61], off offset:16
	global_load_dwordx4 v[170:173], v[60:61], off offset:512
	global_load_dwordx4 v[174:177], v[60:61], off offset:528
	v_lshlrev_b64 v[58:59], 12, v[58:59]
	v_lshl_add_u64 v[58:59], s[62:63], 0, v[58:59]
	v_lshl_add_u64 v[58:59], v[142:143], 1, v[58:59]
	s_waitcnt vmcnt(3)
	v_pk_add_f32 v[52:53], v[48:49], v[52:53]
	v_pk_add_f32 v[50:51], v[46:47], v[50:51]
	s_waitcnt vmcnt(2)
	v_pk_add_f32 v[56:57], v[44:45], v[56:57]
	v_pk_add_f32 v[54:55], v[42:43], v[54:55]
	v_cvt_pk_bf16_f32 v42, v50, v51
	v_cvt_pk_bf16_f32 v43, v52, v53
	v_mul_f32_e32 v51, v51, v51
	v_cvt_pk_bf16_f32 v44, v54, v55
	v_cvt_pk_bf16_f32 v45, v56, v57
	global_store_dwordx4 v[58:59], v[42:45], off
	s_nop 0
	s_nop 0
	s_nop 0
	v_mul_f32_e32 v53, v53, v53
	v_mul_f32_e32 v55, v55, v55
	v_fmac_f32_e32 v51, v50, v50
	v_fmac_f32_e32 v53, v52, v52
	v_mul_f32_e32 v57, v57, v57
	v_fmac_f32_e32 v55, v54, v54
	v_add_f32_e32 v50, v51, v53
	v_fmac_f32_e32 v57, v56, v56
	v_add_f32_e32 v50, v50, v55
	v_add_f32_e32 v50, v57, v50
	s_waitcnt vmcnt(2)
	v_pk_add_f32 v[40:41], v[40:41], v[172:173]
	v_pk_add_f32 v[38:39], v[38:39], v[170:171]
	s_waitcnt vmcnt(1)
	v_pk_add_f32 v[44:45], v[34:35], v[174:175]
	v_mul_f32_e32 v34, v39, v39
	v_mul_f32_e32 v35, v41, v41
	v_pk_add_f32 v[42:43], v[36:37], v[176:177]
	v_mul_f32_e32 v36, v45, v45
	v_fmac_f32_e32 v34, v38, v38
	v_fmac_f32_e32 v35, v40, v40
	v_mul_f32_e32 v37, v43, v43
	v_fmac_f32_e32 v36, v44, v44
	v_add_f32_e32 v34, v34, v35
	v_add_f32_e32 v34, v34, v36
	v_fmac_f32_e32 v37, v42, v42
	v_add_f32_e32 v34, v37, v34
	v_add_f32_e32 v34, v50, v34
	ds_bpermute_b32 v35, v122, v34
	v_cvt_pk_bf16_f32 v36, v38, v39
	v_cvt_pk_bf16_f32 v37, v40, v41
	v_cvt_pk_bf16_f32 v38, v44, v45
	v_cvt_pk_bf16_f32 v39, v42, v43
	s_waitcnt lgkmcnt(0)
	v_add_f32_e32 v34, v34, v35
	ds_bpermute_b32 v35, v116, v34
	global_store_dwordx4 v[58:59], v[36:39], off offset:256
	s_and_saveexec_b64 s[0:1], vcc
	s_cbranch_execz .LBB0_1034
	s_waitcnt lgkmcnt(0)
	v_add_f32_e32 v34, v34, v35
	global_atomic_add_f32 v[114:115], v34, off offset:576
.LBB0_1034:
	s_or_b64 exec, exec, s[0:1]
	v_add_u32_e32 v42, 0xa0, v144
	v_ashrrev_i32_e32 v43, 31, v42
	s_waitcnt lgkmcnt(0)
	v_lshlrev_b64 v[34:35], 13, v[42:43]
	v_lshl_add_u64 v[34:35], s[60:61], 0, v[34:35]
	v_lshl_add_u64 v[44:45], v[142:143], 2, v[34:35]
	global_load_dwordx4 v[34:37], v[44:45], off
	global_load_dwordx4 v[38:41], v[44:45], off offset:16
	global_load_dwordx4 v[170:173], v[44:45], off offset:512
	global_load_dwordx4 v[174:177], v[44:45], off offset:528
	v_lshlrev_b64 v[42:43], 12, v[42:43]
	v_lshl_add_u64 v[42:43], s[62:63], 0, v[42:43]
	v_lshl_add_u64 v[42:43], v[142:143], 1, v[42:43]
	s_waitcnt vmcnt(3)
	v_pk_add_f32 v[36:37], v[32:33], v[36:37]
	v_pk_add_f32 v[34:35], v[30:31], v[34:35]
	s_waitcnt vmcnt(2)
	v_pk_add_f32 v[40:41], v[28:29], v[40:41]
	v_pk_add_f32 v[38:39], v[26:27], v[38:39]
	v_cvt_pk_bf16_f32 v26, v34, v35
	v_cvt_pk_bf16_f32 v27, v36, v37
	v_mul_f32_e32 v35, v35, v35
	v_cvt_pk_bf16_f32 v28, v38, v39
	v_cvt_pk_bf16_f32 v29, v40, v41
	global_store_dwordx4 v[42:43], v[26:29], off
	s_nop 0
	s_nop 0
	s_nop 0
	v_mul_f32_e32 v37, v37, v37
	v_mul_f32_e32 v39, v39, v39
	v_fmac_f32_e32 v35, v34, v34
	v_fmac_f32_e32 v37, v36, v36
	v_mul_f32_e32 v41, v41, v41
	v_fmac_f32_e32 v39, v38, v38
	v_add_f32_e32 v34, v35, v37
	v_fmac_f32_e32 v41, v40, v40
	v_add_f32_e32 v34, v34, v39
	v_add_f32_e32 v34, v41, v34
	s_waitcnt vmcnt(2)
	v_pk_add_f32 v[24:25], v[24:25], v[172:173]
	v_pk_add_f32 v[22:23], v[22:23], v[170:171]
	s_waitcnt vmcnt(1)
	v_pk_add_f32 v[28:29], v[18:19], v[174:175]
	v_mul_f32_e32 v18, v23, v23
	v_mul_f32_e32 v19, v25, v25
	v_pk_add_f32 v[26:27], v[20:21], v[176:177]
	v_mul_f32_e32 v20, v29, v29
	v_fmac_f32_e32 v18, v22, v22
	v_fmac_f32_e32 v19, v24, v24
	v_mul_f32_e32 v21, v27, v27
	v_fmac_f32_e32 v20, v28, v28
	v_add_f32_e32 v18, v18, v19
	v_add_f32_e32 v18, v18, v20
	v_fmac_f32_e32 v21, v26, v26
	v_add_f32_e32 v18, v21, v18
	v_add_f32_e32 v18, v34, v18
	ds_bpermute_b32 v19, v122, v18
	v_cvt_pk_bf16_f32 v20, v22, v23
	v_cvt_pk_bf16_f32 v21, v24, v25
	v_cvt_pk_bf16_f32 v22, v28, v29
	v_cvt_pk_bf16_f32 v23, v26, v27
	s_waitcnt lgkmcnt(0)
	v_add_f32_e32 v18, v18, v19
	ds_bpermute_b32 v19, v116, v18
	global_store_dwordx4 v[42:43], v[20:23], off offset:256
	s_and_saveexec_b64 s[0:1], vcc
	s_cbranch_execz .LBB0_1036
	s_waitcnt lgkmcnt(0)
	v_add_f32_e32 v18, v18, v19
	global_atomic_add_f32 v[114:115], v18, off offset:640
.LBB0_1036:
	s_or_b64 exec, exec, s[0:1]
	v_add_u32_e32 v26, 0xb0, v144
	v_ashrrev_i32_e32 v27, 31, v26
	s_waitcnt lgkmcnt(0)
	v_lshlrev_b64 v[18:19], 13, v[26:27]
	v_lshl_add_u64 v[18:19], s[60:61], 0, v[18:19]
	v_lshl_add_u64 v[28:29], v[142:143], 2, v[18:19]
	global_load_dwordx4 v[18:21], v[28:29], off
	global_load_dwordx4 v[22:25], v[28:29], off offset:16
	global_load_dwordx4 v[170:173], v[28:29], off offset:512
	global_load_dwordx4 v[174:177], v[28:29], off offset:528
	v_lshlrev_b64 v[26:27], 12, v[26:27]
	v_lshl_add_u64 v[26:27], s[62:63], 0, v[26:27]
	v_lshl_add_u64 v[26:27], v[142:143], 1, v[26:27]
	s_waitcnt vmcnt(3)
	v_pk_add_f32 v[20:21], v[16:17], v[20:21]
	v_pk_add_f32 v[18:19], v[14:15], v[18:19]
	s_waitcnt vmcnt(2)
	v_pk_add_f32 v[24:25], v[12:13], v[24:25]
	v_pk_add_f32 v[22:23], v[10:11], v[22:23]
	v_cvt_pk_bf16_f32 v10, v18, v19
	v_cvt_pk_bf16_f32 v11, v20, v21
	v_mul_f32_e32 v19, v19, v19
	v_cvt_pk_bf16_f32 v12, v22, v23
	v_cvt_pk_bf16_f32 v13, v24, v25
	global_store_dwordx4 v[26:27], v[10:13], off
	s_nop 0
	s_nop 0
	s_nop 0
	v_mul_f32_e32 v21, v21, v21
	v_mul_f32_e32 v23, v23, v23
	v_fmac_f32_e32 v19, v18, v18
	v_fmac_f32_e32 v21, v20, v20
	v_mul_f32_e32 v25, v25, v25
	v_fmac_f32_e32 v23, v22, v22
	v_add_f32_e32 v18, v19, v21
	v_fmac_f32_e32 v25, v24, v24
	v_add_f32_e32 v18, v18, v23
	v_add_f32_e32 v18, v25, v18
	s_waitcnt vmcnt(2)
	v_pk_add_f32 v[8:9], v[8:9], v[172:173]
	v_pk_add_f32 v[6:7], v[6:7], v[170:171]
	s_waitcnt vmcnt(1)
	v_pk_add_f32 v[12:13], v[2:3], v[174:175]
	v_mul_f32_e32 v2, v7, v7
	v_mul_f32_e32 v3, v9, v9
	v_pk_add_f32 v[10:11], v[4:5], v[176:177]
	v_mul_f32_e32 v4, v13, v13
	v_fmac_f32_e32 v2, v6, v6
	v_fmac_f32_e32 v3, v8, v8
	v_mul_f32_e32 v5, v11, v11
	v_fmac_f32_e32 v4, v12, v12
	v_add_f32_e32 v2, v2, v3
	v_add_f32_e32 v2, v2, v4
	v_fmac_f32_e32 v5, v10, v10
	v_add_f32_e32 v2, v5, v2
	v_add_f32_e32 v2, v18, v2
	ds_bpermute_b32 v3, v122, v2
	v_cvt_pk_bf16_f32 v4, v6, v7
	v_cvt_pk_bf16_f32 v5, v8, v9
	v_cvt_pk_bf16_f32 v6, v12, v13
	v_cvt_pk_bf16_f32 v7, v10, v11
	s_waitcnt lgkmcnt(0)
	v_add_f32_e32 v2, v2, v3
	ds_bpermute_b32 v3, v116, v2
	global_store_dwordx4 v[26:27], v[4:7], off offset:256
	s_and_saveexec_b64 s[0:1], vcc
	s_cbranch_execz .LBB0_1038
	s_waitcnt lgkmcnt(0)
	v_add_f32_e32 v2, v2, v3
	global_atomic_add_f32 v[114:115], v2, off offset:704
